# down-proj and PLE epilogues: residual-tile loads for all row groups issued at K-loop exit to warm L2
# baseline (speedup 1.0000x reference)
; #define PG8_STAGE(bufoff, gbase, voff) do { _Pragma("unroll") for (int _i = 0; _i < 2; ++_i) \
;         __builtin_amdgcn_global_load_lds((const unsigned*)((const char*)(gbase) + (voff)[_i]), (LAS unsigned*)(lds + (bufoff) + ldsw + _i * 8192), 16, 0, 0); } while (0)
; #define PG8_LDA(dst, b, h) do { _Pragma("unroll") for (int m = 0; m < 4; ++m) _Pragma("unroll") for (int k = 0; k < 2; ++k) dst[m][k] = *(const LAS bf16x8*)(lds + PG8_SA(b, h) + aoff + m * 2048 + k * 1024); } while (0)
; #define PG8_LDB(dst, b, h) do { _Pragma("unroll") for (int n = 0; n < 2; ++n) _Pragma("unroll") for (int k = 0; k < 2; ++k) dst[n][k] = *(const LAS bf16x8*)(lds + PG8_SB(b, h) + boff + n * 2048 + k * 1024); } while (0)
; template <class Epi, bool PERMA = false, bool DUAL = false, bool ALIGN_EPI = true, bool SP2 = true>
; __device__ __forceinline__ void gemm_phase(LAS unsigned char* lds, const Gemm g, const StaticOrder& S, const Epi& E) {
;     ...
;         for (int t = 0; t < nt; t += 2) {
;             const bool last = (t == nt - 2);
;             const char* a1 = cA + (size_t)(t + 1) * kstep;
;             const char* a2 = last ? nA : cA + (size_t)(t + 2) * kstep; const char* b2 = last ? nB : cB + (size_t)(t + 2) * kstep;
;             const char* a3 = a2 + kstep; const char* b3 = b2 + kstep;
;             if constexpr (SP2) {
;             PG8_LDB(B0, 0, 0); PG8_LDB(B1, 0, 1); PG8_SCHED; PG8_LDA(At, 0, 0); PG8_STAGE(PG8_SA(1, 1), a1 + hstepA, voffA);
;             PG8_WAIT_V(8); PG8_WAIT_L(0); PG8_BAR; PG8_MMA(0, 0, At, B0); PG8_MMA(0, 1, At, B1); PG8_BAR; PG8_SCHED;
;             PG8_LDA(At, 0, 1); PG8_STAGE(PG8_SB(0, 0), b2, voffB); PG8_STAGE(PG8_SB(0, 1), b2 + hstepB, voffB); PG8_STAGE(PG8_SA(0, 0), a2, voffA);
;             PG8_WAIT_V(8); PG8_WAIT_L(0); PG8_BAR; PG8_MMA(1, 0, At, B0); PG8_MMA(1, 1, At, B1); PG8_BAR; PG8_SCHED;
;             PG8_LDB(B0, 1, 0); PG8_LDB(B1, 1, 1); PG8_SCHED; PG8_LDA(At, 1, 0); PG8_STAGE(PG8_SA(0, 1), a2 + hstepA, voffA);
;             PG8_WAIT_V(8); PG8_WAIT_L(0); PG8_BAR; PG8_MMA(0, 0, At, B0); PG8_MMA(0, 1, At, B1); PG8_BAR; PG8_SCHED;
;             PG8_LDA(At, 1, 1); PG8_STAGE(PG8_SB(1, 0), b3, voffB); PG8_STAGE(PG8_SB(1, 1), b3 + hstepB, voffB); PG8_STAGE(PG8_SA(1, 0), a3, voffA);
;             PG8_WAIT_V(8); PG8_WAIT_L(0); PG8_BAR; PG8_MMA(1, 0, At, B0); PG8_MMA(1, 1, At, B1); PG8_BAR; PG8_SCHED;
.LBB0_675:
	s_add_u32 s14, s12, 0x100
	s_addc_u32 s15, s13, 0
	s_add_i32 s36, 0, 0x10000
	s_cmpk_eq_i32 s33, 0x54
	s_cselect_b32 s19, s1, s15
	s_cselect_b32 s18, s0, s14
	s_cselect_b32 s17, s7, s11
	s_cselect_b32 s16, s6, s9
	s_add_i32 s37, 0, 0x14000
	v_add_u32_e32 v116, s36, v193
	v_add_u32_e32 v156, s37, v193
	ds_read_b128 v[104:107], v116
	ds_read_b128 v[108:111], v116 offset:1024
	ds_read_b128 v[112:115], v116 offset:2048
	ds_read_b128 v[116:119], v116 offset:3072
	ds_read_b128 v[144:147], v156
	ds_read_b128 v[148:151], v156 offset:1024
	ds_read_b128 v[152:155], v156 offset:2048
	ds_read_b128 v[156:159], v156 offset:3072
	v_lshl_add_u64 v[206:207], s[12:13], 0, v[180:181]
	s_add_i32 m0, s21, 0xc000
	ds_read_b128 v[184:187], v212
	ds_read_b128 v[188:191], v212 offset:1024
	ds_read_b128 v[214:217], v212 offset:2048
	ds_read_b128 v[218:221], v212 offset:3072
	ds_read_b128 v[222:225], v212 offset:4096
	ds_read_b128 v[226:229], v212 offset:5120
	ds_read_b128 v[238:241], v212 offset:6144
	ds_read_b128 v[242:245], v212 offset:7168
	global_load_lds_dwordx4 v[206:207], off
	v_lshl_add_u64 v[206:207], s[12:13], 0, v[182:183]
	s_add_i32 m0, s21, 0xe000
	s_nop 0
	global_load_lds_dwordx4 v[206:207], off
	s_waitcnt vmcnt(8)
	s_waitcnt lgkmcnt(0)
	s_barrier
	s_setprio 1
	s_waitcnt lgkmcnt(0)
	v_mfma_f32_16x16x32_bf16 v[140:143], v[104:107], v[184:187], v[140:143]
	v_mfma_f32_16x16x32_bf16 v[136:139], v[112:115], v[184:187], v[136:139]
	v_mfma_f32_16x16x32_bf16 v[124:127], v[104:107], v[214:217], v[124:127]
	v_mfma_f32_16x16x32_bf16 v[120:123], v[112:115], v[214:217], v[120:123]
	v_mfma_f32_16x16x32_bf16 v[92:95], v[104:107], v[222:225], v[92:95]
	v_mfma_f32_16x16x32_bf16 v[88:91], v[112:115], v[222:225], v[88:91]
	v_mfma_f32_16x16x32_bf16 v[76:79], v[104:107], v[238:241], v[76:79]
	v_mfma_f32_16x16x32_bf16 v[72:75], v[112:115], v[238:241], v[72:75]
	v_mfma_f32_16x16x32_bf16 v[140:143], v[108:111], v[188:191], v[140:143]
	v_mfma_f32_16x16x32_bf16 v[136:139], v[116:119], v[188:191], v[136:139]
	v_mfma_f32_16x16x32_bf16 v[124:127], v[108:111], v[218:221], v[124:127]
	v_mfma_f32_16x16x32_bf16 v[120:123], v[116:119], v[218:221], v[120:123]
	v_mfma_f32_16x16x32_bf16 v[92:95], v[108:111], v[226:229], v[92:95]
	v_mfma_f32_16x16x32_bf16 v[88:91], v[116:119], v[226:229], v[88:91]
	v_mfma_f32_16x16x32_bf16 v[76:79], v[108:111], v[242:245], v[76:79]
	v_mfma_f32_16x16x32_bf16 v[72:75], v[116:119], v[242:245], v[72:75]
	s_setprio 0
	s_setprio 1
	v_mfma_f32_16x16x32_bf16 v[132:135], v[144:147], v[184:187], v[132:135]
	v_mfma_f32_16x16x32_bf16 v[128:131], v[152:155], v[184:187], v[128:131]
	v_mfma_f32_16x16x32_bf16 v[100:103], v[144:147], v[214:217], v[100:103]
	v_mfma_f32_16x16x32_bf16 v[96:99], v[152:155], v[214:217], v[96:99]
	v_mfma_f32_16x16x32_bf16 v[84:87], v[144:147], v[222:225], v[84:87]
	v_mfma_f32_16x16x32_bf16 v[80:83], v[152:155], v[222:225], v[80:83]
	v_mfma_f32_16x16x32_bf16 v[68:71], v[144:147], v[238:241], v[68:71]
	v_mfma_f32_16x16x32_bf16 v[64:67], v[152:155], v[238:241], v[64:67]
	v_mfma_f32_16x16x32_bf16 v[132:135], v[148:151], v[188:191], v[132:135]
	v_mfma_f32_16x16x32_bf16 v[128:131], v[156:159], v[188:191], v[128:131]
	v_mfma_f32_16x16x32_bf16 v[100:103], v[148:151], v[218:221], v[100:103]
	v_mfma_f32_16x16x32_bf16 v[96:99], v[156:159], v[218:221], v[96:99]
	v_mfma_f32_16x16x32_bf16 v[84:87], v[148:151], v[226:229], v[84:87]
	v_mfma_f32_16x16x32_bf16 v[80:83], v[156:159], v[226:229], v[80:83]
	v_mfma_f32_16x16x32_bf16 v[68:71], v[148:151], v[242:245], v[68:71]
	v_mfma_f32_16x16x32_bf16 v[64:67], v[156:159], v[242:245], v[64:67]
	s_setprio 0
	s_barrier
	s_add_i32 s12, s36, s20
	v_lshl_add_u64 v[206:207], s[16:17], 0, v[164:165]
	s_mov_b32 m0, s12
	ds_read_b128 v[184:187], v212 offset:16384
	ds_read_b128 v[188:191], v212 offset:17408
	ds_read_b128 v[214:217], v212 offset:18432
	ds_read_b128 v[218:221], v212 offset:19456
	ds_read_b128 v[222:225], v212 offset:20480
	ds_read_b128 v[226:229], v212 offset:21504
	ds_read_b128 v[238:241], v212 offset:22528
	ds_read_b128 v[242:245], v212 offset:23552
	global_load_lds_dwordx4 v[206:207], off
	s_add_i32 m0, s12, 0x2000
	s_add_u32 s12, s16, 0x160000
	v_lshl_add_u64 v[246:247], s[16:17], 0, v[160:161]
	s_addc_u32 s13, s17, 0
	s_add_i32 s36, s37, s20
	global_load_lds_dwordx4 v[246:247], off
	v_lshl_add_u64 v[248:249], s[12:13], 0, v[164:165]
	s_mov_b32 m0, s36
	v_lshl_add_u64 v[194:195], s[18:19], 0, v[162:163]
	global_load_lds_dwordx4 v[248:249], off
	v_lshl_add_u64 v[248:249], s[12:13], 0, v[160:161]
	s_add_i32 m0, s36, 0x2000
	s_nop 0
	global_load_lds_dwordx4 v[248:249], off
	v_lshl_add_u64 v[248:249], s[18:19], 0, v[166:167]
	s_mov_b32 m0, s21
	s_nop 0
	global_load_lds_dwordx4 v[248:249], off
	s_mov_b32 m0, s22
	s_nop 0
	global_load_lds_dwordx4 v[194:195], off
	s_waitcnt vmcnt(8)
	s_waitcnt lgkmcnt(0)
	s_barrier
; #define PG8_STAGE(bufoff, gbase, voff) do { _Pragma("unroll") for (int _i = 0; _i < 2; ++_i) \
;         __builtin_amdgcn_global_load_lds((const unsigned*)((const char*)(gbase) + (voff)[_i]), (LAS unsigned*)(lds + (bufoff) + ldsw + _i * 8192), 16, 0, 0); } while (0)
; #define PG8_LDA(dst, b, h) do { _Pragma("unroll") for (int m = 0; m < 4; ++m) _Pragma("unroll") for (int k = 0; k < 2; ++k) dst[m][k] = *(const LAS bf16x8*)(lds + PG8_SA(b, h) + aoff + m * 2048 + k * 1024); } while (0)
; #define PG8_LDB(dst, b, h) do { _Pragma("unroll") for (int n = 0; n < 2; ++n) _Pragma("unroll") for (int k = 0; k < 2; ++k) dst[n][k] = *(const LAS bf16x8*)(lds + PG8_SB(b, h) + boff + n * 2048 + k * 1024); } while (0)
; #define PG8_MMA(ai, bj, At, Bt) do { __builtin_amdgcn_s_setprio(1); _Pragma("unroll") for (int m = 0; m < 4; ++m) _Pragma("unroll") for (int n = 0; n < 2; ++n) _Pragma("unroll") for (int k = 0; k < 2; ++k) \
;         acc[ai][bj][m][n] = __builtin_amdgcn_mfma_f32_16x16x32_bf16(Bt[n][k], At[m][k], acc[ai][bj][m][n], 0, 0, 0); __builtin_amdgcn_s_setprio(0); } while (0)
; #define PG8_WAIT_V(n) asm volatile("s_waitcnt vmcnt(" #n ")" ::: "memory")
; #define PG8_WAIT_L(n) asm volatile("s_waitcnt lgkmcnt(" #n ")" ::: "memory")
; template <class Epi, bool PERMA = false, bool DUAL = false, bool ALIGN_EPI = true, bool SP2 = true>
; __device__ __forceinline__ void gemm_phase(LAS unsigned char* lds, const Gemm g, const StaticOrder& S, const Epi& E) {
;     ...
;             PG8_WAIT_V(8); PG8_WAIT_L(0); PG8_BAR; PG8_MMA(0, 0, At, B0); PG8_MMA(0, 1, At, B1); PG8_BAR; PG8_SCHED;
;             PG8_LDA(At, 0, 1); PG8_STAGE(PG8_SB(0, 0), b2, voffB); PG8_STAGE(PG8_SB(0, 1), b2 + hstepB, voffB); PG8_STAGE(PG8_SA(0, 0), a2, voffA);
;             PG8_WAIT_V(8); PG8_WAIT_L(0); PG8_BAR; PG8_MMA(1, 0, At, B0); PG8_MMA(1, 1, At, B1); PG8_BAR; PG8_SCHED;
;             PG8_LDB(B0, 1, 0); PG8_LDB(B1, 1, 1); PG8_SCHED; PG8_LDA(At, 1, 0); PG8_STAGE(PG8_SA(0, 1), a2 + hstepA, voffA);
;             PG8_WAIT_V(8); PG8_WAIT_L(0); PG8_BAR; PG8_MMA(0, 0, At, B0); PG8_MMA(0, 1, At, B1); PG8_BAR; PG8_SCHED;
;             PG8_LDA(At, 1, 1); PG8_STAGE(PG8_SB(1, 0), b3, voffB); PG8_STAGE(PG8_SB(1, 1), b3 + hstepB, voffB); PG8_STAGE(PG8_SA(1, 0), a3, voffA);
;             PG8_WAIT_V(8); PG8_WAIT_L(0); PG8_BAR; PG8_MMA(1, 0, At, B0); PG8_MMA(1, 1, At, B1); PG8_BAR; PG8_SCHED;
	s_setprio 1
	s_waitcnt lgkmcnt(0)
	v_mfma_f32_16x16x32_bf16 v[60:63], v[104:107], v[184:187], v[60:63]
	v_mfma_f32_16x16x32_bf16 v[56:59], v[112:115], v[184:187], v[56:59]
	v_mfma_f32_16x16x32_bf16 v[44:47], v[104:107], v[214:217], v[44:47]
	v_mfma_f32_16x16x32_bf16 v[40:43], v[112:115], v[214:217], v[40:43]
	v_mfma_f32_16x16x32_bf16 v[28:31], v[104:107], v[222:225], v[28:31]
	v_mfma_f32_16x16x32_bf16 v[24:27], v[112:115], v[222:225], v[24:27]
	v_mfma_f32_16x16x32_bf16 v[12:15], v[104:107], v[238:241], v[12:15]
	v_mfma_f32_16x16x32_bf16 v[8:11], v[112:115], v[238:241], v[8:11]
	v_mfma_f32_16x16x32_bf16 v[60:63], v[108:111], v[188:191], v[60:63]
	v_mfma_f32_16x16x32_bf16 v[56:59], v[116:119], v[188:191], v[56:59]
	v_mfma_f32_16x16x32_bf16 v[44:47], v[108:111], v[218:221], v[44:47]
	v_mfma_f32_16x16x32_bf16 v[40:43], v[116:119], v[218:221], v[40:43]
	v_mfma_f32_16x16x32_bf16 v[28:31], v[108:111], v[226:229], v[28:31]
	v_mfma_f32_16x16x32_bf16 v[24:27], v[116:119], v[226:229], v[24:27]
	v_mfma_f32_16x16x32_bf16 v[12:15], v[108:111], v[242:245], v[12:15]
	v_mfma_f32_16x16x32_bf16 v[8:11], v[116:119], v[242:245], v[8:11]
	s_setprio 0
	s_setprio 1
	v_mfma_f32_16x16x32_bf16 v[52:55], v[144:147], v[184:187], v[52:55]
	v_mfma_f32_16x16x32_bf16 v[48:51], v[152:155], v[184:187], v[48:51]
	v_mfma_f32_16x16x32_bf16 v[36:39], v[144:147], v[214:217], v[36:39]
	v_mfma_f32_16x16x32_bf16 v[32:35], v[152:155], v[214:217], v[32:35]
	v_mfma_f32_16x16x32_bf16 v[20:23], v[144:147], v[222:225], v[20:23]
	v_mfma_f32_16x16x32_bf16 v[16:19], v[152:155], v[222:225], v[16:19]
	v_mfma_f32_16x16x32_bf16 v[4:7], v[144:147], v[238:241], v[4:7]
	v_mfma_f32_16x16x32_bf16 v[0:3], v[152:155], v[238:241], v[0:3]
	v_mfma_f32_16x16x32_bf16 v[52:55], v[148:151], v[188:191], v[52:55]
	v_mfma_f32_16x16x32_bf16 v[48:51], v[156:159], v[188:191], v[48:51]
	v_mfma_f32_16x16x32_bf16 v[36:39], v[148:151], v[218:221], v[36:39]
	v_mfma_f32_16x16x32_bf16 v[32:35], v[156:159], v[218:221], v[32:35]
	v_mfma_f32_16x16x32_bf16 v[20:23], v[148:151], v[226:229], v[20:23]
	v_mfma_f32_16x16x32_bf16 v[16:19], v[156:159], v[226:229], v[16:19]
	v_mfma_f32_16x16x32_bf16 v[4:7], v[148:151], v[242:245], v[4:7]
	v_mfma_f32_16x16x32_bf16 v[0:3], v[156:159], v[242:245], v[0:3]
	s_setprio 0
	s_barrier
	s_add_i32 s36, 0, 0x18000
	s_add_i32 s37, 0, 0x1c000
	v_add_u32_e32 v116, s36, v193
	v_add_u32_e32 v156, s37, v193
	ds_read_b128 v[104:107], v116
	ds_read_b128 v[108:111], v116 offset:1024
	ds_read_b128 v[112:115], v116 offset:2048
	ds_read_b128 v[116:119], v116 offset:3072
	ds_read_b128 v[144:147], v156
	ds_read_b128 v[148:151], v156 offset:1024
	ds_read_b128 v[152:155], v156 offset:2048
	ds_read_b128 v[156:159], v156 offset:3072
	s_add_u32 s12, s18, 0x160000
	s_addc_u32 s13, s19, 0
	s_mov_b32 m0, s23
	v_lshl_add_u64 v[196:197], s[12:13], 0, v[166:167]
	ds_read_b128 v[184:187], v212 offset:32768
	ds_read_b128 v[188:191], v212 offset:33792
	ds_read_b128 v[214:217], v212 offset:34816
	ds_read_b128 v[218:221], v212 offset:35840
	ds_read_b128 v[222:225], v212 offset:36864
	ds_read_b128 v[226:229], v212 offset:37888
	ds_read_b128 v[238:241], v212 offset:38912
	ds_read_b128 v[242:245], v212 offset:39936
	global_load_lds_dwordx4 v[196:197], off
	v_lshl_add_u64 v[196:197], s[12:13], 0, v[162:163]
	s_mov_b32 m0, s24
	s_nop 0
	global_load_lds_dwordx4 v[196:197], off
	s_waitcnt vmcnt(8)
	s_waitcnt lgkmcnt(0)
	s_barrier
	s_setprio 1
	s_waitcnt lgkmcnt(0)
	v_mfma_f32_16x16x32_bf16 v[140:143], v[104:107], v[184:187], v[140:143]
	v_mfma_f32_16x16x32_bf16 v[136:139], v[112:115], v[184:187], v[136:139]
	v_mfma_f32_16x16x32_bf16 v[124:127], v[104:107], v[214:217], v[124:127]
	v_mfma_f32_16x16x32_bf16 v[120:123], v[112:115], v[214:217], v[120:123]
	v_mfma_f32_16x16x32_bf16 v[92:95], v[104:107], v[222:225], v[92:95]
	v_mfma_f32_16x16x32_bf16 v[88:91], v[112:115], v[222:225], v[88:91]
	v_mfma_f32_16x16x32_bf16 v[76:79], v[104:107], v[238:241], v[76:79]
	v_mfma_f32_16x16x32_bf16 v[72:75], v[112:115], v[238:241], v[72:75]
	v_mfma_f32_16x16x32_bf16 v[140:143], v[108:111], v[188:191], v[140:143]
	v_mfma_f32_16x16x32_bf16 v[136:139], v[116:119], v[188:191], v[136:139]
	v_mfma_f32_16x16x32_bf16 v[124:127], v[108:111], v[218:221], v[124:127]
	v_mfma_f32_16x16x32_bf16 v[120:123], v[116:119], v[218:221], v[120:123]
	v_mfma_f32_16x16x32_bf16 v[92:95], v[108:111], v[226:229], v[92:95]
	v_mfma_f32_16x16x32_bf16 v[88:91], v[116:119], v[226:229], v[88:91]
	v_mfma_f32_16x16x32_bf16 v[76:79], v[108:111], v[242:245], v[76:79]
	v_mfma_f32_16x16x32_bf16 v[72:75], v[116:119], v[242:245], v[72:75]
	s_setprio 0
	s_setprio 1
	v_mfma_f32_16x16x32_bf16 v[132:135], v[144:147], v[184:187], v[132:135]
	v_mfma_f32_16x16x32_bf16 v[128:131], v[152:155], v[184:187], v[128:131]
	v_mfma_f32_16x16x32_bf16 v[100:103], v[144:147], v[214:217], v[100:103]
	v_mfma_f32_16x16x32_bf16 v[96:99], v[152:155], v[214:217], v[96:99]
	v_mfma_f32_16x16x32_bf16 v[84:87], v[144:147], v[222:225], v[84:87]
	v_mfma_f32_16x16x32_bf16 v[80:83], v[152:155], v[222:225], v[80:83]
	v_mfma_f32_16x16x32_bf16 v[68:71], v[144:147], v[238:241], v[68:71]
	v_mfma_f32_16x16x32_bf16 v[64:67], v[152:155], v[238:241], v[64:67]
	v_mfma_f32_16x16x32_bf16 v[132:135], v[148:151], v[188:191], v[132:135]
	v_mfma_f32_16x16x32_bf16 v[128:131], v[156:159], v[188:191], v[128:131]
	v_mfma_f32_16x16x32_bf16 v[100:103], v[148:151], v[218:221], v[100:103]
	v_mfma_f32_16x16x32_bf16 v[96:99], v[156:159], v[218:221], v[96:99]
	v_mfma_f32_16x16x32_bf16 v[84:87], v[148:151], v[226:229], v[84:87]
	v_mfma_f32_16x16x32_bf16 v[80:83], v[156:159], v[226:229], v[80:83]
	v_mfma_f32_16x16x32_bf16 v[68:71], v[148:151], v[242:245], v[68:71]
	v_mfma_f32_16x16x32_bf16 v[64:67], v[156:159], v[242:245], v[64:67]
	s_setprio 0
	s_barrier
; #define PG8_STAGE(bufoff, gbase, voff) do { _Pragma("unroll") for (int _i = 0; _i < 2; ++_i) \
;         __builtin_amdgcn_global_load_lds((const unsigned*)((const char*)(gbase) + (voff)[_i]), (LAS unsigned*)(lds + (bufoff) + ldsw + _i * 8192), 16, 0, 0); } while (0)
; #define PG8_LDA(dst, b, h) do { _Pragma("unroll") for (int m = 0; m < 4; ++m) _Pragma("unroll") for (int k = 0; k < 2; ++k) dst[m][k] = *(const LAS bf16x8*)(lds + PG8_SA(b, h) + aoff + m * 2048 + k * 1024); } while (0)
; #define PG8_LDB(dst, b, h) do { _Pragma("unroll") for (int n = 0; n < 2; ++n) _Pragma("unroll") for (int k = 0; k < 2; ++k) dst[n][k] = *(const LAS bf16x8*)(lds + PG8_SB(b, h) + boff + n * 2048 + k * 1024); } while (0)
; #define PG8_MMA(ai, bj, At, Bt) do { __builtin_amdgcn_s_setprio(1); _Pragma("unroll") for (int m = 0; m < 4; ++m) _Pragma("unroll") for (int n = 0; n < 2; ++n) _Pragma("unroll") for (int k = 0; k < 2; ++k) \
;         acc[ai][bj][m][n] = __builtin_amdgcn_mfma_f32_16x16x32_bf16(Bt[n][k], At[m][k], acc[ai][bj][m][n], 0, 0, 0); __builtin_amdgcn_s_setprio(0); } while (0)
; #define PG8_WAIT_V(n) asm volatile("s_waitcnt vmcnt(" #n ")" ::: "memory")
; #define PG8_WAIT_L(n) asm volatile("s_waitcnt lgkmcnt(" #n ")" ::: "memory")
; #define PG8_BAR __builtin_amdgcn_s_barrier()
; #define PG8_SCHED __builtin_amdgcn_sched_barrier(0)
; template <class Epi, bool PERMA = false, bool DUAL = false, bool ALIGN_EPI = true, bool SP2 = true>
; __device__ __forceinline__ void gemm_phase(LAS unsigned char* lds, const Gemm g, const StaticOrder& S, const Epi& E) {
;     ...
;             PG8_LDB(B0, 1, 0); PG8_LDB(B1, 1, 1); PG8_SCHED; PG8_LDA(At, 1, 0); PG8_STAGE(PG8_SA(0, 1), a2 + hstepA, voffA);
;             PG8_WAIT_V(8); PG8_WAIT_L(0); PG8_BAR; PG8_MMA(0, 0, At, B0); PG8_MMA(0, 1, At, B1); PG8_BAR; PG8_SCHED;
;             PG8_LDA(At, 1, 1); PG8_STAGE(PG8_SB(1, 0), b3, voffB); PG8_STAGE(PG8_SB(1, 1), b3 + hstepB, voffB); PG8_STAGE(PG8_SA(1, 0), a3, voffA);
;             PG8_WAIT_V(8); PG8_WAIT_L(0); PG8_BAR; PG8_MMA(1, 0, At, B0); PG8_MMA(1, 1, At, B1); PG8_BAR; PG8_SCHED;
;     __device__ __forceinline__ void operator()(const f32x4 (&acc)[2][2][4][2], const Unit& u, int wr, int wc, int fr, int fq) const {
;     ...
;         ED_LOAD(0, 0);
; #pragma unroll
;         for (int grp = 0; grp < 8; ++grp) {
;             if (grp < 7) ED_LOAD((grp + 1) & 1, grp + 1);
	s_add_i32 s12, s36, s20
	v_lshl_add_u64 v[196:197], v[206:207], 0, s[38:39]
	s_mov_b32 m0, s12
	ds_read_b128 v[184:187], v212 offset:49152
	ds_read_b128 v[188:191], v212 offset:50176
	ds_read_b128 v[214:217], v212 offset:51200
	ds_read_b128 v[218:221], v212 offset:52224
	ds_read_b128 v[222:225], v212 offset:53248
	ds_read_b128 v[226:229], v212 offset:54272
	ds_read_b128 v[238:241], v212 offset:55296
	ds_read_b128 v[242:245], v212 offset:56320
	global_load_lds_dwordx4 v[196:197], off
	s_add_i32 m0, s12, 0x2000
	s_add_u32 s12, s16, 0x160080
	v_lshl_add_u64 v[196:197], v[246:247], 0, s[38:39]
	s_addc_u32 s13, s17, 0
	s_add_i32 s16, s37, s20
	global_load_lds_dwordx4 v[196:197], off
	v_lshl_add_u64 v[196:197], s[12:13], 0, v[164:165]
	s_mov_b32 m0, s16
	v_lshl_add_u64 v[194:195], v[194:195], 0, s[38:39]
	global_load_lds_dwordx4 v[196:197], off
	v_lshl_add_u64 v[196:197], s[12:13], 0, v[160:161]
	s_add_i32 m0, s16, 0x2000
	s_nop 0
	global_load_lds_dwordx4 v[196:197], off
	v_lshl_add_u64 v[196:197], v[248:249], 0, s[38:39]
	s_mov_b32 m0, s29
	s_nop 0
	global_load_lds_dwordx4 v[196:197], off
	s_mov_b32 m0, s30
	s_nop 0
	global_load_lds_dwordx4 v[194:195], off
	s_waitcnt vmcnt(8)
	s_waitcnt lgkmcnt(0)
	s_barrier
	s_setprio 1
	s_waitcnt lgkmcnt(0)
	v_mfma_f32_16x16x32_bf16 v[60:63], v[104:107], v[184:187], v[60:63]
	v_mfma_f32_16x16x32_bf16 v[56:59], v[112:115], v[184:187], v[56:59]
	v_mfma_f32_16x16x32_bf16 v[44:47], v[104:107], v[214:217], v[44:47]
	v_mfma_f32_16x16x32_bf16 v[40:43], v[112:115], v[214:217], v[40:43]
	v_mfma_f32_16x16x32_bf16 v[28:31], v[104:107], v[222:225], v[28:31]
	v_mfma_f32_16x16x32_bf16 v[24:27], v[112:115], v[222:225], v[24:27]
	v_mfma_f32_16x16x32_bf16 v[12:15], v[104:107], v[238:241], v[12:15]
	v_mfma_f32_16x16x32_bf16 v[8:11], v[112:115], v[238:241], v[8:11]
	v_mfma_f32_16x16x32_bf16 v[60:63], v[108:111], v[188:191], v[60:63]
	v_mfma_f32_16x16x32_bf16 v[56:59], v[116:119], v[188:191], v[56:59]
	v_mfma_f32_16x16x32_bf16 v[44:47], v[108:111], v[218:221], v[44:47]
	v_mfma_f32_16x16x32_bf16 v[40:43], v[116:119], v[218:221], v[40:43]
	v_mfma_f32_16x16x32_bf16 v[28:31], v[108:111], v[226:229], v[28:31]
	v_mfma_f32_16x16x32_bf16 v[24:27], v[116:119], v[226:229], v[24:27]
	v_mfma_f32_16x16x32_bf16 v[12:15], v[108:111], v[242:245], v[12:15]
	v_mfma_f32_16x16x32_bf16 v[8:11], v[116:119], v[242:245], v[8:11]
	s_setprio 0
	s_setprio 1
	v_mfma_f32_16x16x32_bf16 v[52:55], v[144:147], v[184:187], v[52:55]
	v_mfma_f32_16x16x32_bf16 v[48:51], v[152:155], v[184:187], v[48:51]
	v_mfma_f32_16x16x32_bf16 v[36:39], v[144:147], v[214:217], v[36:39]
	v_mfma_f32_16x16x32_bf16 v[32:35], v[152:155], v[214:217], v[32:35]
	v_mfma_f32_16x16x32_bf16 v[20:23], v[144:147], v[222:225], v[20:23]
	v_mfma_f32_16x16x32_bf16 v[16:19], v[152:155], v[222:225], v[16:19]
	v_mfma_f32_16x16x32_bf16 v[4:7], v[144:147], v[238:241], v[4:7]
	v_mfma_f32_16x16x32_bf16 v[0:3], v[152:155], v[238:241], v[0:3]
	v_mfma_f32_16x16x32_bf16 v[52:55], v[148:151], v[188:191], v[52:55]
	v_mfma_f32_16x16x32_bf16 v[48:51], v[156:159], v[188:191], v[48:51]
	v_mfma_f32_16x16x32_bf16 v[36:39], v[148:151], v[218:221], v[36:39]
	v_mfma_f32_16x16x32_bf16 v[32:35], v[156:159], v[218:221], v[32:35]
	v_mfma_f32_16x16x32_bf16 v[20:23], v[148:151], v[226:229], v[20:23]
	v_mfma_f32_16x16x32_bf16 v[16:19], v[156:159], v[226:229], v[16:19]
	v_mfma_f32_16x16x32_bf16 v[4:7], v[148:151], v[242:245], v[4:7]
	v_mfma_f32_16x16x32_bf16 v[0:3], v[156:159], v[242:245], v[0:3]
	s_setprio 0
	s_barrier
	s_add_i32 s33, s33, 2
	s_add_u32 s9, s9, 0x100
	s_addc_u32 s11, s11, 0
	s_cmpk_gt_u32 s33, 0x55
	s_mov_b64 s[12:13], s[14:15]
	s_cbranch_scc0 .LBB0_675
	s_lshl_b32 s14, s10, 8
	s_add_i32 s14, s14, s27
	s_lshl_b32 s16, s8, 8
	s_ashr_i32 s15, s14, 31
	s_or_b32 s16, s16, s28
	s_ashr_i32 s17, s16, 31
	s_lshl_b64 s[14:15], s[14:15], 11
	s_add_u32 s14, s14, s16
	s_addc_u32 s15, s15, s17
	s_lshl_b64 s[14:15], s[14:15], 2
	s_add_u32 s14, s76, s14
	s_addc_u32 s15, s77, s15
	global_load_dwordx4 v[246:249], v170, s[14:15]
	global_load_dwordx4 v[246:249], v170, s[14:15] offset:512
	s_add_u32 s14, s14, 0x20000
	s_addc_u32 s15, s15, 0
	global_load_dwordx4 v[246:249], v170, s[14:15]
	global_load_dwordx4 v[246:249], v170, s[14:15] offset:512
	s_add_u32 s14, s14, 0x20000
	s_addc_u32 s15, s15, 0
	global_load_dwordx4 v[246:249], v170, s[14:15]
	global_load_dwordx4 v[246:249], v170, s[14:15] offset:512
	s_add_u32 s14, s14, 0x20000
	s_addc_u32 s15, s15, 0
	global_load_dwordx4 v[246:249], v170, s[14:15]
	global_load_dwordx4 v[246:249], v170, s[14:15] offset:512
	s_add_u32 s14, s14, 0xa0000
	s_addc_u32 s15, s15, 0
	global_load_dwordx4 v[246:249], v170, s[14:15]
	global_load_dwordx4 v[246:249], v170, s[14:15] offset:512
	s_add_u32 s14, s14, 0x20000
	s_addc_u32 s15, s15, 0
	global_load_dwordx4 v[246:249], v170, s[14:15]
	global_load_dwordx4 v[246:249], v170, s[14:15] offset:512
	s_add_u32 s14, s14, 0x20000
	s_addc_u32 s15, s15, 0
	global_load_dwordx4 v[246:249], v170, s[14:15]
	global_load_dwordx4 v[246:249], v170, s[14:15] offset:512
	s_add_u32 s14, s14, 0x20000
	s_addc_u32 s15, s15, 0
	global_load_dwordx4 v[246:249], v170, s[14:15]
	global_load_dwordx4 v[246:249], v170, s[14:15] offset:512
	s_and_b64 vcc, exec, s[4:5]
	s_cbranch_vccz .LBB0_678
	s_barrier

; #define PG8_STAGE(bufoff, gbase, voff) do { _Pragma("unroll") for (int _i = 0; _i < 2; ++_i) \
;         __builtin_amdgcn_global_load_lds((const unsigned*)((const char*)(gbase) + (voff)[_i]), (LAS unsigned*)(lds + (bufoff) + ldsw + _i * 8192), 16, 0, 0); } while (0)
; #define PG8_LDA(dst, b, h) do { _Pragma("unroll") for (int m = 0; m < 4; ++m) _Pragma("unroll") for (int k = 0; k < 2; ++k) dst[m][k] = *(const LAS bf16x8*)(lds + PG8_SA(b, h) + aoff + m * 2048 + k * 1024); } while (0)
; #define PG8_LDB(dst, b, h) do { _Pragma("unroll") for (int n = 0; n < 2; ++n) _Pragma("unroll") for (int k = 0; k < 2; ++k) dst[n][k] = *(const LAS bf16x8*)(lds + PG8_SB(b, h) + boff + n * 2048 + k * 1024); } while (0)
; #define PG8_MMA(ai, bj, At, Bt) do { __builtin_amdgcn_s_setprio(1); _Pragma("unroll") for (int m = 0; m < 4; ++m) _Pragma("unroll") for (int n = 0; n < 2; ++n) _Pragma("unroll") for (int k = 0; k < 2; ++k) \
;         acc[ai][bj][m][n] = __builtin_amdgcn_mfma_f32_16x16x32_bf16(Bt[n][k], At[m][k], acc[ai][bj][m][n], 0, 0, 0); __builtin_amdgcn_s_setprio(0); } while (0)
; #define PG8_WAIT_V(n) asm volatile("s_waitcnt vmcnt(" #n ")" ::: "memory")
; #define PG8_WAIT_L(n) asm volatile("s_waitcnt lgkmcnt(" #n ")" ::: "memory")
; template <class Epi, bool PERMA = false, bool DUAL = false, bool ALIGN_EPI = true, bool SP2 = true>
; __device__ __forceinline__ void gemm_phase(LAS unsigned char* lds, const Gemm g, const StaticOrder& S, const Epi& E) {
;     ...
;         for (int t = 0; t < nt; t += 2) {
;             const bool last = (t == nt - 2);
;             const char* a1 = cA + (size_t)(t + 1) * kstep;
;             const char* a2 = last ? nA : cA + (size_t)(t + 2) * kstep; const char* b2 = last ? nB : cB + (size_t)(t + 2) * kstep;
;             const char* a3 = a2 + kstep; const char* b3 = b2 + kstep;
;             if constexpr (SP2) {
;             PG8_LDB(B0, 0, 0); PG8_LDB(B1, 0, 1); PG8_SCHED; PG8_LDA(At, 0, 0); PG8_STAGE(PG8_SA(1, 1), a1 + hstepA, voffA);
;             PG8_WAIT_V(8); PG8_WAIT_L(0); PG8_BAR; PG8_MMA(0, 0, At, B0); PG8_MMA(0, 1, At, B1); PG8_BAR; PG8_SCHED;
;             PG8_LDA(At, 0, 1); PG8_STAGE(PG8_SB(0, 0), b2, voffB); PG8_STAGE(PG8_SB(0, 1), b2 + hstepB, voffB); PG8_STAGE(PG8_SA(0, 0), a2, voffA);
;             PG8_WAIT_V(8); PG8_WAIT_L(0); PG8_BAR; PG8_MMA(1, 0, At, B0); PG8_MMA(1, 1, At, B1); PG8_BAR; PG8_SCHED;
.LBB0_790:
	s_add_u32 s14, s12, 0xfff80080
	s_addc_u32 s15, s13, -1
	s_add_i32 s36, 0, 0x10000
	s_cmp_eq_u32 s35, 28
	s_cselect_b32 s17, s7, s15
	s_cselect_b32 s16, s30, s14
	s_cselect_b32 s15, s5, s34
	s_cselect_b32 s14, s31, s33
	s_add_i32 s40, 0, 0x14000
	v_add_u32_e32 v140, s36, v190
	v_add_u32_e32 v156, s40, v190
	ds_read_b128 v[120:123], v140
	ds_read_b128 v[128:131], v140 offset:1024
	ds_read_b128 v[132:135], v140 offset:2048
	ds_read_b128 v[140:143], v140 offset:3072
	ds_read_b128 v[144:147], v156
	ds_read_b128 v[148:151], v156 offset:1024
	ds_read_b128 v[152:155], v156 offset:2048
	ds_read_b128 v[156:159], v156 offset:3072
	v_lshl_add_u64 v[194:195], s[12:13], 0, v[174:175]
	s_add_i32 m0, s19, 0xc000
	ds_read_b128 v[178:181], v191
	ds_read_b128 v[182:185], v191 offset:1024
	ds_read_b128 v[186:189], v191 offset:2048
	ds_read_b128 v[206:209], v191 offset:3072
	ds_read_b128 v[210:213], v191 offset:4096
	ds_read_b128 v[214:217], v191 offset:5120
	ds_read_b128 v[218:221], v191 offset:6144
	ds_read_b128 v[222:225], v191 offset:7168
	global_load_lds_dwordx4 v[194:195], off
	v_lshl_add_u64 v[194:195], s[12:13], 0, v[176:177]
	s_add_i32 m0, s19, 0xe000
	s_nop 0
	global_load_lds_dwordx4 v[194:195], off
	s_waitcnt vmcnt(8)
	s_waitcnt lgkmcnt(0)
	s_barrier
	s_setprio 1
	s_waitcnt lgkmcnt(0)
	v_mfma_f32_16x16x32_bf16 v[136:139], v[120:123], v[178:181], v[136:139]
	v_mfma_f32_16x16x32_bf16 v[124:127], v[132:135], v[178:181], v[124:127]
	v_mfma_f32_16x16x32_bf16 v[108:111], v[120:123], v[186:189], v[108:111]
	v_mfma_f32_16x16x32_bf16 v[104:107], v[132:135], v[186:189], v[104:107]
	v_mfma_f32_16x16x32_bf16 v[92:95], v[120:123], v[210:213], v[92:95]
	v_mfma_f32_16x16x32_bf16 v[88:91], v[132:135], v[210:213], v[88:91]
	v_mfma_f32_16x16x32_bf16 v[76:79], v[120:123], v[218:221], v[76:79]
	v_mfma_f32_16x16x32_bf16 v[72:75], v[132:135], v[218:221], v[72:75]
	v_mfma_f32_16x16x32_bf16 v[136:139], v[128:131], v[182:185], v[136:139]
	v_mfma_f32_16x16x32_bf16 v[124:127], v[140:143], v[182:185], v[124:127]
	v_mfma_f32_16x16x32_bf16 v[108:111], v[128:131], v[206:209], v[108:111]
	v_mfma_f32_16x16x32_bf16 v[104:107], v[140:143], v[206:209], v[104:107]
	v_mfma_f32_16x16x32_bf16 v[92:95], v[128:131], v[214:217], v[92:95]
	v_mfma_f32_16x16x32_bf16 v[88:91], v[140:143], v[214:217], v[88:91]
	v_mfma_f32_16x16x32_bf16 v[76:79], v[128:131], v[222:225], v[76:79]
	v_mfma_f32_16x16x32_bf16 v[72:75], v[140:143], v[222:225], v[72:75]
	s_setprio 0
	s_setprio 1
	v_mfma_f32_16x16x32_bf16 v[116:119], v[144:147], v[178:181], v[116:119]
	v_mfma_f32_16x16x32_bf16 v[112:115], v[152:155], v[178:181], v[112:115]
	v_mfma_f32_16x16x32_bf16 v[100:103], v[144:147], v[186:189], v[100:103]
	v_mfma_f32_16x16x32_bf16 v[96:99], v[152:155], v[186:189], v[96:99]
	v_mfma_f32_16x16x32_bf16 v[84:87], v[144:147], v[210:213], v[84:87]
	v_mfma_f32_16x16x32_bf16 v[80:83], v[152:155], v[210:213], v[80:83]
	v_mfma_f32_16x16x32_bf16 v[68:71], v[144:147], v[218:221], v[68:71]
	v_mfma_f32_16x16x32_bf16 v[64:67], v[152:155], v[218:221], v[64:67]
	v_mfma_f32_16x16x32_bf16 v[116:119], v[148:151], v[182:185], v[116:119]
	v_mfma_f32_16x16x32_bf16 v[112:115], v[156:159], v[182:185], v[112:115]
	v_mfma_f32_16x16x32_bf16 v[100:103], v[148:151], v[206:209], v[100:103]
	v_mfma_f32_16x16x32_bf16 v[96:99], v[156:159], v[206:209], v[96:99]
	v_mfma_f32_16x16x32_bf16 v[84:87], v[148:151], v[214:217], v[84:87]
	v_mfma_f32_16x16x32_bf16 v[80:83], v[156:159], v[214:217], v[80:83]
	v_mfma_f32_16x16x32_bf16 v[68:71], v[148:151], v[222:225], v[68:71]
	v_mfma_f32_16x16x32_bf16 v[64:67], v[156:159], v[222:225], v[64:67]
	s_setprio 0
	s_barrier
	s_add_i32 s36, s36, s18
	v_lshl_add_u64 v[194:195], s[14:15], 0, v[164:165]
	s_mov_b32 m0, s36
	ds_read_b128 v[178:181], v191 offset:16384
	ds_read_b128 v[182:185], v191 offset:17408
	ds_read_b128 v[186:189], v191 offset:18432
	ds_read_b128 v[206:209], v191 offset:19456
	ds_read_b128 v[210:213], v191 offset:20480
	ds_read_b128 v[214:217], v191 offset:21504
	ds_read_b128 v[218:221], v191 offset:22528
	ds_read_b128 v[222:225], v191 offset:23552
	global_load_lds_dwordx4 v[194:195], off
	s_add_i32 m0, s36, 0x2000
	s_add_u32 s36, s14, 0x80000
	v_lshl_add_u64 v[196:197], s[14:15], 0, v[160:161]
	s_addc_u32 s37, s15, 0
	s_add_i32 s40, s40, s18
	global_load_lds_dwordx4 v[196:197], off
	v_lshl_add_u64 v[226:227], s[36:37], 0, v[164:165]
	s_mov_b32 m0, s40
	v_lshl_add_u64 v[228:229], s[16:17], 0, v[162:163]
	global_load_lds_dwordx4 v[226:227], off
	v_lshl_add_u64 v[226:227], s[36:37], 0, v[160:161]
	s_add_i32 m0, s40, 0x2000
	s_nop 0
	global_load_lds_dwordx4 v[226:227], off
	v_lshl_add_u64 v[226:227], s[16:17], 0, v[166:167]
	s_mov_b32 m0, s19
	s_nop 0
	global_load_lds_dwordx4 v[226:227], off
	s_mov_b32 m0, s20
	s_nop 0
	global_load_lds_dwordx4 v[228:229], off
	s_waitcnt vmcnt(8)
	s_waitcnt lgkmcnt(0)
	s_barrier
; #define PG8_STAGE(bufoff, gbase, voff) do { _Pragma("unroll") for (int _i = 0; _i < 2; ++_i) \
;         __builtin_amdgcn_global_load_lds((const unsigned*)((const char*)(gbase) + (voff)[_i]), (LAS unsigned*)(lds + (bufoff) + ldsw + _i * 8192), 16, 0, 0); } while (0)
; #define PG8_LDA(dst, b, h) do { _Pragma("unroll") for (int m = 0; m < 4; ++m) _Pragma("unroll") for (int k = 0; k < 2; ++k) dst[m][k] = *(const LAS bf16x8*)(lds + PG8_SA(b, h) + aoff + m * 2048 + k * 1024); } while (0)
; #define PG8_LDB(dst, b, h) do { _Pragma("unroll") for (int n = 0; n < 2; ++n) _Pragma("unroll") for (int k = 0; k < 2; ++k) dst[n][k] = *(const LAS bf16x8*)(lds + PG8_SB(b, h) + boff + n * 2048 + k * 1024); } while (0)
; #define PG8_MMA(ai, bj, At, Bt) do { __builtin_amdgcn_s_setprio(1); _Pragma("unroll") for (int m = 0; m < 4; ++m) _Pragma("unroll") for (int n = 0; n < 2; ++n) _Pragma("unroll") for (int k = 0; k < 2; ++k) \
;         acc[ai][bj][m][n] = __builtin_amdgcn_mfma_f32_16x16x32_bf16(Bt[n][k], At[m][k], acc[ai][bj][m][n], 0, 0, 0); __builtin_amdgcn_s_setprio(0); } while (0)
; #define PG8_WAIT_V(n) asm volatile("s_waitcnt vmcnt(" #n ")" ::: "memory")
; #define PG8_WAIT_L(n) asm volatile("s_waitcnt lgkmcnt(" #n ")" ::: "memory")
; template <class Epi, bool PERMA = false, bool DUAL = false, bool ALIGN_EPI = true, bool SP2 = true>
; __device__ __forceinline__ void gemm_phase(LAS unsigned char* lds, const Gemm g, const StaticOrder& S, const Epi& E) {
;     ...
;             PG8_WAIT_V(8); PG8_WAIT_L(0); PG8_BAR; PG8_MMA(0, 0, At, B0); PG8_MMA(0, 1, At, B1); PG8_BAR; PG8_SCHED;
;             PG8_LDA(At, 0, 1); PG8_STAGE(PG8_SB(0, 0), b2, voffB); PG8_STAGE(PG8_SB(0, 1), b2 + hstepB, voffB); PG8_STAGE(PG8_SA(0, 0), a2, voffA);
;             PG8_WAIT_V(8); PG8_WAIT_L(0); PG8_BAR; PG8_MMA(1, 0, At, B0); PG8_MMA(1, 1, At, B1); PG8_BAR; PG8_SCHED;
;             PG8_LDB(B0, 1, 0); PG8_LDB(B1, 1, 1); PG8_SCHED; PG8_LDA(At, 1, 0); PG8_STAGE(PG8_SA(0, 1), a2 + hstepA, voffA);
;             PG8_WAIT_V(8); PG8_WAIT_L(0); PG8_BAR; PG8_MMA(0, 0, At, B0); PG8_MMA(0, 1, At, B1); PG8_BAR; PG8_SCHED;
;             PG8_LDA(At, 1, 1); PG8_STAGE(PG8_SB(1, 0), b3, voffB); PG8_STAGE(PG8_SB(1, 1), b3 + hstepB, voffB); PG8_STAGE(PG8_SA(1, 0), a3, voffA);
;             PG8_WAIT_V(8); PG8_WAIT_L(0); PG8_BAR; PG8_MMA(1, 0, At, B0); PG8_MMA(1, 1, At, B1); PG8_BAR; PG8_SCHED;
	s_setprio 1
	s_waitcnt lgkmcnt(0)
	v_mfma_f32_16x16x32_bf16 v[60:63], v[120:123], v[178:181], v[60:63]
	v_mfma_f32_16x16x32_bf16 v[56:59], v[132:135], v[178:181], v[56:59]
	v_mfma_f32_16x16x32_bf16 v[44:47], v[120:123], v[186:189], v[44:47]
	v_mfma_f32_16x16x32_bf16 v[40:43], v[132:135], v[186:189], v[40:43]
	v_mfma_f32_16x16x32_bf16 v[28:31], v[120:123], v[210:213], v[28:31]
	v_mfma_f32_16x16x32_bf16 v[24:27], v[132:135], v[210:213], v[24:27]
	v_mfma_f32_16x16x32_bf16 v[12:15], v[120:123], v[218:221], v[12:15]
	v_mfma_f32_16x16x32_bf16 v[8:11], v[132:135], v[218:221], v[8:11]
	v_mfma_f32_16x16x32_bf16 v[60:63], v[128:131], v[182:185], v[60:63]
	v_mfma_f32_16x16x32_bf16 v[56:59], v[140:143], v[182:185], v[56:59]
	v_mfma_f32_16x16x32_bf16 v[44:47], v[128:131], v[206:209], v[44:47]
	v_mfma_f32_16x16x32_bf16 v[40:43], v[140:143], v[206:209], v[40:43]
	v_mfma_f32_16x16x32_bf16 v[28:31], v[128:131], v[214:217], v[28:31]
	v_mfma_f32_16x16x32_bf16 v[24:27], v[140:143], v[214:217], v[24:27]
	v_mfma_f32_16x16x32_bf16 v[12:15], v[128:131], v[222:225], v[12:15]
	v_mfma_f32_16x16x32_bf16 v[8:11], v[140:143], v[222:225], v[8:11]
	s_setprio 0
	s_setprio 1
	v_mfma_f32_16x16x32_bf16 v[52:55], v[144:147], v[178:181], v[52:55]
	v_mfma_f32_16x16x32_bf16 v[48:51], v[152:155], v[178:181], v[48:51]
	v_mfma_f32_16x16x32_bf16 v[36:39], v[144:147], v[186:189], v[36:39]
	v_mfma_f32_16x16x32_bf16 v[32:35], v[152:155], v[186:189], v[32:35]
	v_mfma_f32_16x16x32_bf16 v[20:23], v[144:147], v[210:213], v[20:23]
	v_mfma_f32_16x16x32_bf16 v[16:19], v[152:155], v[210:213], v[16:19]
	v_mfma_f32_16x16x32_bf16 v[0:3], v[144:147], v[218:221], v[0:3]
	v_mfma_f32_16x16x32_bf16 v[4:7], v[152:155], v[218:221], v[4:7]
	v_mfma_f32_16x16x32_bf16 v[52:55], v[148:151], v[182:185], v[52:55]
	v_mfma_f32_16x16x32_bf16 v[48:51], v[156:159], v[182:185], v[48:51]
	v_mfma_f32_16x16x32_bf16 v[36:39], v[148:151], v[206:209], v[36:39]
	v_mfma_f32_16x16x32_bf16 v[32:35], v[156:159], v[206:209], v[32:35]
	v_mfma_f32_16x16x32_bf16 v[20:23], v[148:151], v[214:217], v[20:23]
	v_mfma_f32_16x16x32_bf16 v[16:19], v[156:159], v[214:217], v[16:19]
	v_mfma_f32_16x16x32_bf16 v[0:3], v[148:151], v[222:225], v[0:3]
	v_mfma_f32_16x16x32_bf16 v[4:7], v[156:159], v[222:225], v[4:7]
	s_setprio 0
	s_barrier
	s_add_i32 s36, 0, 0x18000
	s_add_i32 s37, 0, 0x1c000
	v_add_u32_e32 v140, s36, v190
	v_add_u32_e32 v156, s37, v190
	ds_read_b128 v[120:123], v140
	ds_read_b128 v[128:131], v140 offset:1024
	ds_read_b128 v[132:135], v140 offset:2048
	ds_read_b128 v[140:143], v140 offset:3072
	ds_read_b128 v[144:147], v156
	ds_read_b128 v[148:151], v156 offset:1024
	ds_read_b128 v[152:155], v156 offset:2048
	ds_read_b128 v[156:159], v156 offset:3072
	s_add_u32 s16, s16, 0x80000
	s_addc_u32 s17, s17, 0
	s_mov_b32 m0, s21
	v_lshl_add_u64 v[238:239], s[16:17], 0, v[166:167]
	ds_read_b128 v[178:181], v191 offset:32768
	ds_read_b128 v[182:185], v191 offset:33792
	ds_read_b128 v[186:189], v191 offset:34816
	ds_read_b128 v[206:209], v191 offset:35840
	ds_read_b128 v[210:213], v191 offset:36864
	ds_read_b128 v[214:217], v191 offset:37888
	ds_read_b128 v[218:221], v191 offset:38912
	ds_read_b128 v[222:225], v191 offset:39936
	global_load_lds_dwordx4 v[238:239], off
	v_lshl_add_u64 v[238:239], s[16:17], 0, v[162:163]
	s_mov_b32 m0, s22
	s_nop 0
	global_load_lds_dwordx4 v[238:239], off
	s_waitcnt vmcnt(8)
	s_waitcnt lgkmcnt(0)
	s_barrier
	s_setprio 1
	s_waitcnt lgkmcnt(0)
	v_mfma_f32_16x16x32_bf16 v[136:139], v[120:123], v[178:181], v[136:139]
	v_mfma_f32_16x16x32_bf16 v[124:127], v[132:135], v[178:181], v[124:127]
	v_mfma_f32_16x16x32_bf16 v[108:111], v[120:123], v[186:189], v[108:111]
	v_mfma_f32_16x16x32_bf16 v[104:107], v[132:135], v[186:189], v[104:107]
	v_mfma_f32_16x16x32_bf16 v[92:95], v[120:123], v[210:213], v[92:95]
	v_mfma_f32_16x16x32_bf16 v[88:91], v[132:135], v[210:213], v[88:91]
	v_mfma_f32_16x16x32_bf16 v[76:79], v[120:123], v[218:221], v[76:79]
	v_mfma_f32_16x16x32_bf16 v[72:75], v[132:135], v[218:221], v[72:75]
	v_mfma_f32_16x16x32_bf16 v[136:139], v[128:131], v[182:185], v[136:139]
	v_mfma_f32_16x16x32_bf16 v[124:127], v[140:143], v[182:185], v[124:127]
	v_mfma_f32_16x16x32_bf16 v[108:111], v[128:131], v[206:209], v[108:111]
	v_mfma_f32_16x16x32_bf16 v[104:107], v[140:143], v[206:209], v[104:107]
	v_mfma_f32_16x16x32_bf16 v[92:95], v[128:131], v[214:217], v[92:95]
	v_mfma_f32_16x16x32_bf16 v[88:91], v[140:143], v[214:217], v[88:91]
	v_mfma_f32_16x16x32_bf16 v[76:79], v[128:131], v[222:225], v[76:79]
	v_mfma_f32_16x16x32_bf16 v[72:75], v[140:143], v[222:225], v[72:75]
	s_setprio 0
	s_setprio 1
	v_mfma_f32_16x16x32_bf16 v[116:119], v[144:147], v[178:181], v[116:119]
	v_mfma_f32_16x16x32_bf16 v[112:115], v[152:155], v[178:181], v[112:115]
	v_mfma_f32_16x16x32_bf16 v[100:103], v[144:147], v[186:189], v[100:103]
	v_mfma_f32_16x16x32_bf16 v[96:99], v[152:155], v[186:189], v[96:99]
	v_mfma_f32_16x16x32_bf16 v[84:87], v[144:147], v[210:213], v[84:87]
	v_mfma_f32_16x16x32_bf16 v[80:83], v[152:155], v[210:213], v[80:83]
	v_mfma_f32_16x16x32_bf16 v[68:71], v[144:147], v[218:221], v[68:71]
	v_mfma_f32_16x16x32_bf16 v[64:67], v[152:155], v[218:221], v[64:67]
	v_mfma_f32_16x16x32_bf16 v[116:119], v[148:151], v[182:185], v[116:119]
	v_mfma_f32_16x16x32_bf16 v[112:115], v[156:159], v[182:185], v[112:115]
	v_mfma_f32_16x16x32_bf16 v[100:103], v[148:151], v[206:209], v[100:103]
	v_mfma_f32_16x16x32_bf16 v[96:99], v[156:159], v[206:209], v[96:99]
	v_mfma_f32_16x16x32_bf16 v[84:87], v[148:151], v[214:217], v[84:87]
	v_mfma_f32_16x16x32_bf16 v[80:83], v[156:159], v[214:217], v[80:83]
	v_mfma_f32_16x16x32_bf16 v[68:71], v[148:151], v[222:225], v[68:71]
	v_mfma_f32_16x16x32_bf16 v[64:67], v[156:159], v[222:225], v[64:67]
	s_setprio 0
	s_barrier
; #define PG8_STAGE(bufoff, gbase, voff) do { _Pragma("unroll") for (int _i = 0; _i < 2; ++_i) \
;         __builtin_amdgcn_global_load_lds((const unsigned*)((const char*)(gbase) + (voff)[_i]), (LAS unsigned*)(lds + (bufoff) + ldsw + _i * 8192), 16, 0, 0); } while (0)
; #define PG8_LDA(dst, b, h) do { _Pragma("unroll") for (int m = 0; m < 4; ++m) _Pragma("unroll") for (int k = 0; k < 2; ++k) dst[m][k] = *(const LAS bf16x8*)(lds + PG8_SA(b, h) + aoff + m * 2048 + k * 1024); } while (0)
; #define PG8_LDB(dst, b, h) do { _Pragma("unroll") for (int n = 0; n < 2; ++n) _Pragma("unroll") for (int k = 0; k < 2; ++k) dst[n][k] = *(const LAS bf16x8*)(lds + PG8_SB(b, h) + boff + n * 2048 + k * 1024); } while (0)
; #define PG8_MMA(ai, bj, At, Bt) do { __builtin_amdgcn_s_setprio(1); _Pragma("unroll") for (int m = 0; m < 4; ++m) _Pragma("unroll") for (int n = 0; n < 2; ++n) _Pragma("unroll") for (int k = 0; k < 2; ++k) \
;         acc[ai][bj][m][n] = __builtin_amdgcn_mfma_f32_16x16x32_bf16(Bt[n][k], At[m][k], acc[ai][bj][m][n], 0, 0, 0); __builtin_amdgcn_s_setprio(0); } while (0)
; #define PG8_WAIT_V(n) asm volatile("s_waitcnt vmcnt(" #n ")" ::: "memory")
; #define PG8_WAIT_L(n) asm volatile("s_waitcnt lgkmcnt(" #n ")" ::: "memory")
; #define PG8_BAR __builtin_amdgcn_s_barrier()
; #define PG8_SCHED __builtin_amdgcn_sched_barrier(0)
; template <class Epi, bool PERMA = false, bool DUAL = false, bool ALIGN_EPI = true, bool SP2 = true>
; __device__ __forceinline__ void gemm_phase(LAS unsigned char* lds, const Gemm g, const StaticOrder& S, const Epi& E) {
;     ...
;             PG8_LDB(B0, 1, 0); PG8_LDB(B1, 1, 1); PG8_SCHED; PG8_LDA(At, 1, 0); PG8_STAGE(PG8_SA(0, 1), a2 + hstepA, voffA);
;             PG8_WAIT_V(8); PG8_WAIT_L(0); PG8_BAR; PG8_MMA(0, 0, At, B0); PG8_MMA(0, 1, At, B1); PG8_BAR; PG8_SCHED;
;             PG8_LDA(At, 1, 1); PG8_STAGE(PG8_SB(1, 0), b3, voffB); PG8_STAGE(PG8_SB(1, 1), b3 + hstepB, voffB); PG8_STAGE(PG8_SA(1, 0), a3, voffA);
;             PG8_WAIT_V(8); PG8_WAIT_L(0); PG8_BAR; PG8_MMA(1, 0, At, B0); PG8_MMA(1, 1, At, B1); PG8_BAR; PG8_SCHED;
;     __device__ __forceinline__ void operator()(const f32x4 (&acc)[2][2][4][2], const Unit& u, int wr, int wc, int fr, int fq) const {
;     ...
;         EP_LOAD(0, 0);
; #pragma unroll
;         for (int grp = 0; grp < 8; ++grp) {
;             if (grp < 7) EP_LOAD((grp + 1) & 1, grp + 1);
	s_add_i32 s16, s36, s18
	v_lshl_add_u64 v[194:195], v[194:195], 0, s[46:47]
	s_mov_b32 m0, s16
	ds_read_b128 v[178:181], v191 offset:49152
	ds_read_b128 v[182:185], v191 offset:50176
	ds_read_b128 v[186:189], v191 offset:51200
	ds_read_b128 v[206:209], v191 offset:52224
	ds_read_b128 v[210:213], v191 offset:53248
	ds_read_b128 v[214:217], v191 offset:54272
	ds_read_b128 v[218:221], v191 offset:55296
	ds_read_b128 v[222:225], v191 offset:56320
	global_load_lds_dwordx4 v[194:195], off
	s_add_i32 m0, s16, 0x2000
	s_add_u32 s14, s14, 0x80080
	v_lshl_add_u64 v[194:195], v[196:197], 0, s[46:47]
	s_addc_u32 s15, s15, 0
	s_add_i32 s16, s37, s18
	global_load_lds_dwordx4 v[194:195], off
	v_lshl_add_u64 v[194:195], s[14:15], 0, v[164:165]
	s_mov_b32 m0, s16
	s_nop 0
	global_load_lds_dwordx4 v[194:195], off
	v_lshl_add_u64 v[194:195], s[14:15], 0, v[160:161]
	s_add_i32 m0, s16, 0x2000
	s_nop 0
	global_load_lds_dwordx4 v[194:195], off
	v_lshl_add_u64 v[194:195], v[226:227], 0, s[46:47]
	s_mov_b32 m0, s25
	s_nop 0
	global_load_lds_dwordx4 v[194:195], off
	v_lshl_add_u64 v[194:195], v[228:229], 0, s[46:47]
	s_mov_b32 m0, s26
	s_nop 0
	global_load_lds_dwordx4 v[194:195], off
	s_waitcnt vmcnt(8)
	s_waitcnt lgkmcnt(0)
	s_barrier
	s_setprio 1
	s_waitcnt lgkmcnt(0)
	v_mfma_f32_16x16x32_bf16 v[60:63], v[120:123], v[178:181], v[60:63]
	v_mfma_f32_16x16x32_bf16 v[56:59], v[132:135], v[178:181], v[56:59]
	v_mfma_f32_16x16x32_bf16 v[44:47], v[120:123], v[186:189], v[44:47]
	v_mfma_f32_16x16x32_bf16 v[40:43], v[132:135], v[186:189], v[40:43]
	v_mfma_f32_16x16x32_bf16 v[28:31], v[120:123], v[210:213], v[28:31]
	v_mfma_f32_16x16x32_bf16 v[24:27], v[132:135], v[210:213], v[24:27]
	v_mfma_f32_16x16x32_bf16 v[12:15], v[120:123], v[218:221], v[12:15]
	v_mfma_f32_16x16x32_bf16 v[8:11], v[132:135], v[218:221], v[8:11]
	v_mfma_f32_16x16x32_bf16 v[60:63], v[128:131], v[182:185], v[60:63]
	v_mfma_f32_16x16x32_bf16 v[56:59], v[140:143], v[182:185], v[56:59]
	v_mfma_f32_16x16x32_bf16 v[44:47], v[128:131], v[206:209], v[44:47]
	v_mfma_f32_16x16x32_bf16 v[40:43], v[140:143], v[206:209], v[40:43]
	v_mfma_f32_16x16x32_bf16 v[28:31], v[128:131], v[214:217], v[28:31]
	v_mfma_f32_16x16x32_bf16 v[24:27], v[140:143], v[214:217], v[24:27]
	v_mfma_f32_16x16x32_bf16 v[12:15], v[128:131], v[222:225], v[12:15]
	v_mfma_f32_16x16x32_bf16 v[8:11], v[140:143], v[222:225], v[8:11]
	s_setprio 0
	s_setprio 1
	v_mfma_f32_16x16x32_bf16 v[52:55], v[144:147], v[178:181], v[52:55]
	v_mfma_f32_16x16x32_bf16 v[48:51], v[152:155], v[178:181], v[48:51]
	v_mfma_f32_16x16x32_bf16 v[36:39], v[144:147], v[186:189], v[36:39]
	v_mfma_f32_16x16x32_bf16 v[32:35], v[152:155], v[186:189], v[32:35]
	v_mfma_f32_16x16x32_bf16 v[20:23], v[144:147], v[210:213], v[20:23]
	v_mfma_f32_16x16x32_bf16 v[16:19], v[152:155], v[210:213], v[16:19]
	v_mfma_f32_16x16x32_bf16 v[0:3], v[144:147], v[218:221], v[0:3]
	v_mfma_f32_16x16x32_bf16 v[4:7], v[152:155], v[218:221], v[4:7]
	v_mfma_f32_16x16x32_bf16 v[52:55], v[148:151], v[182:185], v[52:55]
	v_mfma_f32_16x16x32_bf16 v[48:51], v[156:159], v[182:185], v[48:51]
	v_mfma_f32_16x16x32_bf16 v[36:39], v[148:151], v[206:209], v[36:39]
	v_mfma_f32_16x16x32_bf16 v[32:35], v[156:159], v[206:209], v[32:35]
	v_mfma_f32_16x16x32_bf16 v[20:23], v[148:151], v[214:217], v[20:23]
	v_mfma_f32_16x16x32_bf16 v[16:19], v[156:159], v[214:217], v[16:19]
	v_mfma_f32_16x16x32_bf16 v[0:3], v[148:151], v[222:225], v[0:3]
	v_mfma_f32_16x16x32_bf16 v[4:7], v[156:159], v[222:225], v[4:7]
	s_setprio 0
	s_barrier
	s_add_i32 s35, s35, 2
	s_add_u32 s12, s12, 0x100
	s_addc_u32 s13, s13, 0
	s_add_u32 s33, s33, 0x100
	s_addc_u32 s34, s34, 0
	s_cmp_gt_u32 s35, 29
	s_cbranch_scc0 .LBB0_790
	s_lshl_b32 s5, s29, 8
	s_add_i32 s12, s5, s23
	s_lshl_b32 s5, s28, 8
	s_ashr_i32 s13, s12, 31
	s_or_b32 s5, s5, s24
	s_lshl_b64 s[12:13], s[12:13], 11
	s_ashr_i32 s7, s5, 31
	s_add_u32 s12, s12, s5
	s_addc_u32 s13, s13, s7
	s_lshl_b64 s[14:15], s[12:13], 2
	v_lshl_add_u64 v[244:245], v[172:173], 0, s[14:15]
	s_mov_b64 s[14:15], 0x20000
	s_mov_b64 s[12:13], 0xa0000
	v_lshl_add_u64 v[244:245], v[244:245], 0, s[14:15]
	global_load_dwordx4 v[246:249], v[244:245], off
	global_load_dwordx4 v[246:249], v[244:245], off offset:512
	v_lshl_add_u64 v[244:245], v[244:245], 0, s[14:15]
	global_load_dwordx4 v[246:249], v[244:245], off
	global_load_dwordx4 v[246:249], v[244:245], off offset:512
	v_lshl_add_u64 v[244:245], v[244:245], 0, s[14:15]
	global_load_dwordx4 v[246:249], v[244:245], off
	global_load_dwordx4 v[246:249], v[244:245], off offset:512
	v_lshl_add_u64 v[244:245], v[244:245], 0, s[12:13]
	global_load_dwordx4 v[246:249], v[244:245], off
	global_load_dwordx4 v[246:249], v[244:245], off offset:512
	v_lshl_add_u64 v[244:245], v[244:245], 0, s[14:15]
	global_load_dwordx4 v[246:249], v[244:245], off
	global_load_dwordx4 v[246:249], v[244:245], off offset:512
	v_lshl_add_u64 v[244:245], v[244:245], 0, s[14:15]
	global_load_dwordx4 v[246:249], v[244:245], off
	global_load_dwordx4 v[246:249], v[244:245], off offset:512
	v_lshl_add_u64 v[244:245], v[244:245], 0, s[14:15]
	global_load_dwordx4 v[246:249], v[244:245], off
	global_load_dwordx4 v[246:249], v[244:245], off offset:512
	s_and_b64 vcc, exec, s[2:3]
	s_cbranch_vccz .LBB0_793
	s_barrier
